# p0a G-matrix items: B-row loads requested at the top of the item with the parameter loads (one cold round trip per item)
# baseline (speedup 1.0000x reference)
.LBB7_177:
	v_ashrrev_i32_e32 v0, 31, v12
	v_lshrrev_b32_e32 v2, 19, v0
	v_add_u32_e32 v2, v12, v2
	v_ashrrev_i32_e32 v2, 13, v2
	v_mul_hi_i32 v3, v2, s37
	v_lshrrev_b32_e32 v4, 31, v3
	v_lshrrev_b32_e32 v3, 2, v3
	v_add_u32_e32 v3, v3, v4
	v_mul_lo_u32 v3, v3, 24
	v_sub_u32_e32 v5, v2, v3
	v_mul_hi_i32 v2, v12, s37
	v_lshrrev_b32_e32 v3, 31, v2
	v_ashrrev_i32_e32 v2, 15, v2
	s_waitcnt vmcnt(17)
	v_add_u32_e32 v18, v2, v3
	v_mad_i32_i24 v2, v18, 24, v5
	v_ashrrev_i32_e32 v3, 31, v2
	s_waitcnt lgkmcnt(0)
	v_lshl_add_u64 v[6:7], v[2:3], 2, s[16:17]
	global_load_dword v9, v[6:7], off
	v_lshrrev_b32_e32 v0, 26, v0
	v_add_u32_e32 v0, v12, v0
	v_ashrrev_i32_e32 v4, 6, v0
	v_and_b32_e32 v8, 63, v4
	v_lshl_or_b32 v6, v2, 6, v8
	v_ashrrev_i32_e32 v7, 31, v6
	s_waitcnt vmcnt(15)
	v_lshlrev_b64 v[20:21], 2, v[6:7]
	v_lshl_add_u64 v[6:7], s[14:15], 0, v[20:21]
	global_load_dword v7, v[6:7], off
	v_lshl_add_u64 v[20:21], s[12:13], 0, v[20:21]
	global_load_dword v6, v[20:21], off
	v_lshlrev_b32_e32 v44, 9, v4
	v_sub_u32_e32 v44, v10, v44
	v_and_b32_e32 v44, 8, v44
	v_lshlrev_b32_e32 v44, 2, v44
	v_mov_b32_e32 v45, 0
	v_lshlrev_b64 v[46:47], 12, v[2:3]
	v_lshl_or_b32 v46, v8, 6, v46
	v_lshl_add_u64 v[48:49], s[18:19], 0, v[46:47]
	v_lshl_add_u64 v[50:51], s[26:27], 0, v[46:47]
	v_lshl_add_u64 v[48:49], v[48:49], 0, v[44:45]
	v_lshl_add_u64 v[50:51], v[50:51], 0, v[44:45]
	global_load_dwordx4 v[52:55], v[48:49], off
	global_load_dwordx4 v[56:59], v[48:49], off offset:16
	global_load_dwordx4 v[60:63], v[50:51], off
	global_load_dwordx4 v[64:67], v[50:51], off offset:16
	s_waitcnt vmcnt(6)
	v_mul_f32_e32 v0, 0x3fb8aa3b, v9
	v_fma_f32 v19, v9, s38, -v0
	v_rndne_f32_e32 v20, v0
	v_fmac_f32_e32 v19, 0x32a5705f, v9
	v_sub_f32_e32 v0, v0, v20
	v_add_f32_e32 v0, v0, v19
	v_cvt_i32_f32_e32 v20, v20
	v_exp_f32_e32 v0, v0
	v_cmp_ngt_f32_e32 vcc, s39, v9
	v_ldexp_f32 v0, v0, v20
	s_nop 0
	v_cndmask_b32_e32 v0, 0, v0, vcc
	v_cmp_nlt_f32_e32 vcc, s40, v9
	s_nop 1
	v_cndmask_b32_e32 v21, v11, v0, vcc
	s_waitcnt vmcnt(5)
	v_mul_f32_e32 v9, v7, v21
	v_and_b32_e32 v20, 0x7fffffff, v9
	v_lshrrev_b32_e32 v0, 23, v20
	v_and_b32_e32 v19, 0x7fffff, v20
	v_cmp_nlt_f32_e64 s[30:31], |v9|, s41
	v_add_u32_e32 v24, 0xffffff88, v0
	v_or_b32_e32 v19, 0x800000, v19
	s_and_saveexec_b64 s[6:7], s[30:31]
	s_xor_b64 s[34:35], exec, s[6:7]
	s_cbranch_execz .LBB7_179
	v_cmp_lt_u32_e32 vcc, 63, v24
	s_nop 1
	v_cndmask_b32_e32 v0, 0, v15, vcc
	v_add_u32_e32 v0, v0, v24
	v_cmp_lt_u32_e64 s[6:7], 31, v0
	s_nop 1
	v_cndmask_b32_e64 v22, 0, v16, s[6:7]
	v_add_u32_e32 v0, v22, v0
	v_cmp_lt_u32_e64 s[8:9], 31, v0
	s_nop 1
	v_cndmask_b32_e64 v22, 0, v16, s[8:9]
	v_add_u32_e32 v25, v22, v0
	v_mad_u64_u32 v[22:23], s[10:11], v19, s42, 0
	v_mov_b32_e32 v0, v23
	v_mad_u64_u32 v[26:27], s[10:11], v19, s43, v[0:1]
	v_mov_b32_e32 v0, v27
	v_mad_u64_u32 v[28:29], s[10:11], v19, s44, v[0:1]
	v_mov_b32_e32 v0, v29
	v_mad_u64_u32 v[30:31], s[10:11], v19, s45, v[0:1]
	v_mov_b32_e32 v0, v31
	v_mad_u64_u32 v[32:33], s[10:11], v19, s46, v[0:1]
	v_mov_b32_e32 v0, v33
	v_mad_u64_u32 v[34:35], s[10:11], v19, s47, v[0:1]
	v_mov_b32_e32 v0, v35
	v_mad_u64_u32 v[36:37], s[10:11], v19, s48, v[0:1]
	v_cndmask_b32_e32 v23, v34, v30, vcc
	v_cndmask_b32_e32 v0, v36, v32, vcc
	v_cndmask_b32_e32 v29, v37, v34, vcc
	v_cndmask_b32_e64 v27, v0, v23, s[6:7]
	v_cndmask_b32_e64 v0, v29, v0, s[6:7]
	v_cndmask_b32_e32 v29, v32, v28, vcc
	v_cndmask_b32_e64 v23, v23, v29, s[6:7]
	v_sub_u32_e32 v31, 32, v25
	v_cmp_eq_u32_e64 s[10:11], 0, v25
	v_cndmask_b32_e32 v25, v30, v26, vcc
	v_cndmask_b32_e64 v0, v0, v27, s[8:9]
	v_cndmask_b32_e64 v27, v27, v23, s[8:9]
	v_cndmask_b32_e64 v26, v29, v25, s[6:7]
	v_alignbit_b32 v32, v0, v27, v31
	v_cndmask_b32_e64 v23, v23, v26, s[8:9]
	v_cndmask_b32_e64 v0, v32, v0, s[10:11]
	v_alignbit_b32 v29, v27, v23, v31
	v_cndmask_b32_e32 v22, v28, v22, vcc
	v_cndmask_b32_e64 v27, v29, v27, s[10:11]
	v_bfe_u32 v32, v0, 29, 1
	v_cndmask_b32_e64 v22, v25, v22, s[6:7]
	v_alignbit_b32 v29, v0, v27, 30
	v_sub_u32_e32 v33, 0, v32
	v_cndmask_b32_e64 v22, v26, v22, s[8:9]
	v_xor_b32_e32 v29, v29, v33
	v_alignbit_b32 v25, v23, v22, v31
	v_cndmask_b32_e64 v23, v25, v23, s[10:11]
	v_ffbh_u32_e32 v26, v29
	v_alignbit_b32 v25, v27, v23, 30
	v_min_u32_e32 v26, 32, v26
	v_alignbit_b32 v22, v23, v22, 30
	v_xor_b32_e32 v25, v25, v33
	v_sub_u32_e32 v27, 31, v26
	v_xor_b32_e32 v22, v22, v33
	v_alignbit_b32 v28, v29, v25, v27
	v_alignbit_b32 v22, v25, v22, v27
	v_alignbit_b32 v23, v28, v22, 9
	v_ffbh_u32_e32 v25, v23
	v_min_u32_e32 v25, 32, v25
	v_lshrrev_b32_e32 v30, 29, v0
	v_not_b32_e32 v27, v25
	v_alignbit_b32 v22, v23, v22, v27
	v_lshlrev_b32_e32 v23, 31, v30
	v_or_b32_e32 v27, 0x33000000, v23
	v_add_lshl_u32 v25, v25, v26, 23
	v_lshrrev_b32_e32 v22, 9, v22
	v_sub_u32_e32 v25, v27, v25
	v_or_b32_e32 v23, 0.5, v23
	v_lshlrev_b32_e32 v26, 23, v26
	v_or_b32_e32 v22, v25, v22
	v_lshrrev_b32_e32 v25, 9, v28
	v_sub_u32_e32 v23, v23, v26
	v_or_b32_e32 v23, v25, v23
	v_mul_f32_e32 v25, 0x3fc90fda, v23
	v_fma_f32 v26, v23, s49, -v25
	v_fmac_f32_e32 v26, 0x33a22168, v23
	v_fmac_f32_e32 v26, 0x3fc90fda, v22
	v_lshrrev_b32_e32 v0, 30, v0
	v_add_f32_e32 v22, v25, v26
	v_add_u32_e32 v23, v32, v0

.LBB7_185:
	s_or_b64 exec, exec, s[6:7]
	s_waitcnt vmcnt(4)
	v_mul_f32_e32 v26, v6, v21
	v_mul_f32_e32 v21, 0x3fb8aa3b, v26
	v_fma_f32 v27, v26, s38, -v21
	v_rndne_f32_e32 v28, v21
	v_fmac_f32_e32 v27, 0x32a5705f, v26
	v_sub_f32_e32 v21, v21, v28
	v_add_f32_e32 v21, v21, v27
	v_exp_f32_e32 v21, v21
	v_cvt_i32_f32_e32 v27, v28
	v_mul_f32_e32 v29, v22, v22
	v_fmamk_f32 v30, v29, 0x37d75334, v13
	v_cmp_ngt_f32_e32 vcc, s39, v26
	v_ldexp_f32 v21, v21, v27
	v_fmaak_f32 v30, v29, v30, 0x3d2aabf7
	v_fmamk_f32 v31, v29, 0xb94c1982, v14
	v_cndmask_b32_e32 v21, 0, v21, vcc
	v_cmp_nlt_f32_e32 vcc, s40, v26
	v_fmaak_f32 v30, v29, v30, 0xbf000004
	v_fmaak_f32 v31, v29, v31, 0xbe2aaa9d
	v_cndmask_b32_e32 v27, v11, v21, vcc
	v_lshlrev_b32_e32 v21, 30, v23
	v_and_b32_e32 v23, 1, v23
	v_fma_f32 v30, v29, v30, 1.0
	v_mul_f32_e32 v29, v29, v31
	v_fmac_f32_e32 v22, v22, v29
	v_cmp_eq_u32_e32 vcc, 0, v23
	v_lshlrev_b32_e32 v19, 6, v4
	v_sub_u32_e32 v24, v12, v19
	v_cndmask_b32_e64 v22, -v22, v30, vcc
	v_bitop3_b32 v21, v21, v22, s53 bitop3:0x6c
	v_cmp_class_f32_e64 vcc, v9, s52
	v_ashrrev_i32_e32 v24, 1, v24
	v_xor_b32_e32 v20, v20, v9
	v_cndmask_b32_e32 v29, v17, v21, vcc
	v_mul_f32_e32 v21, v25, v25
	v_fmamk_f32 v22, v21, 0xb94c1982, v14
	v_fmaak_f32 v22, v21, v22, 0xbe2aaa9d
	v_mul_f32_e32 v22, v21, v22
	v_fmac_f32_e32 v25, v25, v22
	v_fmamk_f32 v22, v21, 0x37d75334, v13
	v_fmaak_f32 v22, v21, v22, 0x3d2aabf7
	v_fmaak_f32 v22, v21, v22, 0xbf000004
	v_fma_f32 v21, v21, v22, 1.0
	v_and_b32_e32 v22, 1, v0
	v_lshlrev_b32_e32 v0, 30, v0
	v_and_b32_e32 v0, 0x80000000, v0
	v_xor_b32_e32 v0, v20, v0
	v_sub_u32_e32 v20, 31, v24
	v_cmp_eq_u32_e64 s[6:7], 0, v22
	v_cvt_f32_u32_e32 v24, v20
	v_fma_f32 v20, v27, v29, -1.0
	v_cndmask_b32_e64 v21, v21, v25, s[6:7]
	v_xor_b32_e32 v0, v0, v21
	v_cndmask_b32_e32 v0, v17, v0, vcc
	v_mul_f32_e32 v21, v27, v0
	v_mul_f32_e32 v0, v26, v24
	v_mul_f32_e32 v0, 0x3fb8aa3b, v0
	v_exp_f32_e32 v29, v0
	v_mul_f32_e32 v0, 0.15915494, v9
	v_mul_f32_e32 v0, v0, v24
	v_fract_f32_e32 v0, v0
	v_cos_f32_e32 v9, v0
	v_sin_f32_e32 v30, v0
	v_mov_b32_e32 v0, v7
	v_pk_mul_f32 v[22:23], v[6:7], v[6:7]
	v_pk_mul_f32 v[24:25], v[0:1], v[20:21] op_sel:[0,1] op_sel_hi:[0,0]
	v_pk_fma_f32 v[26:27], v[6:7], v[20:21], v[24:25] op_sel_hi:[0,1,1] neg_lo:[0,0,1] neg_hi:[0,0,1]
	v_pk_add_f32 v[22:23], v[22:23], v[22:23] op_sel:[0,1] op_sel_hi:[0,1]
	v_div_scale_f32 v31, s[6:7], v23, v23, v27
	v_rcp_f32_e32 v32, v31
	v_pk_fma_f32 v[6:7], v[6:7], v[20:21], v[24:25]
	v_mul_f32_e32 v0, v29, v9
	v_mul_f32_e32 v26, v29, v30
	v_fma_f32 v7, -v31, v32, 1.0
	v_fmac_f32_e32 v32, v7, v32
	v_div_scale_f32 v7, vcc, v27, v23, v27
	v_mul_f32_e32 v9, v7, v32
	v_fma_f32 v20, -v31, v9, v7
	v_fmac_f32_e32 v9, v20, v32
	v_div_scale_f32 v20, s[6:7], v22, v22, v6
	v_rcp_f32_e32 v24, v20
	v_fma_f32 v7, -v31, v9, v7
	v_div_fmas_f32 v7, v7, v32, v9
	v_div_fixup_f32 v21, v7, v23, v27
	v_fma_f32 v7, -v20, v24, 1.0
	v_fmac_f32_e32 v24, v7, v24
	v_div_scale_f32 v7, vcc, v6, v22, v6
	v_mul_f32_e32 v9, v7, v24
	v_fma_f32 v23, -v20, v9, v7
	v_fmac_f32_e32 v9, v23, v24
	v_fma_f32 v7, -v20, v9, v7
	v_div_fmas_f32 v7, v7, v24, v9
	v_div_fixup_f32 v20, v7, v22, v6
	v_pk_mul_f32 v[22:23], v[26:27], v[20:21] op_sel:[0,1] op_sel_hi:[0,0]
	v_and_b32_e32 v19, 0x7f, v4
	v_lshlrev_b32_e32 v4, 9, v4
	v_pk_fma_f32 v[6:7], v[0:1], v[20:21], v[22:23] neg_lo:[0,0,1] neg_hi:[0,0,1]
	v_pk_fma_f32 v[20:21], v[0:1], v[20:21], v[22:23] op_sel_hi:[0,1,1]
	v_sub_u32_e32 v4, v10, v4
	v_mov_b32_e32 v7, v21
	v_lshlrev_b64 v[20:21], 12, v[2:3]
	v_and_b32_e32 v28, 8, v4
	v_lshl_or_b32 v20, v8, 6, v20
	v_lshl_add_u64 v[2:3], s[18:19], 0, v[20:21]
	v_lshlrev_b32_e32 v0, 2, v28
	v_lshl_add_u64 v[8:9], s[26:27], 0, v[20:21]
	v_lshl_add_u64 v[2:3], v[2:3], 0, v[0:1]
	v_lshl_add_u64 v[8:9], v[8:9], 0, v[0:1]
	v_cmp_lt_u32_e32 vcc, 63, v19
	s_nop 1
	v_bfrev_b32_e32 v27, 1
	v_cndmask_b32_e32 v27, v27, v1, vcc
	s_waitcnt vmcnt(0)
	v_cndmask_b32_e32 v8, v52, v60, vcc
	v_cndmask_b32_e32 v9, v60, v52, vcc
	v_mul_f32_e32 v8, v6, v8
	v_mul_f32_e32 v9, v7, v9
	v_xor_b32_e32 v9, v27, v9
	v_add_f32_e32 v0, v8, v9
	v_cndmask_b32_e32 v8, v53, v61, vcc
	v_cndmask_b32_e32 v9, v61, v53, vcc
	v_mul_f32_e32 v8, v6, v8
	v_mul_f32_e32 v9, v7, v9
	v_xor_b32_e32 v9, v27, v9
	v_add_f32_e32 v20, v8, v9
	v_cndmask_b32_e32 v8, v54, v62, vcc
	v_cndmask_b32_e32 v9, v62, v54, vcc
	v_mul_f32_e32 v8, v6, v8
	v_mul_f32_e32 v9, v7, v9
	v_xor_b32_e32 v9, v27, v9
	v_add_f32_e32 v21, v8, v9
	v_cndmask_b32_e32 v8, v55, v63, vcc
	v_cndmask_b32_e32 v9, v63, v55, vcc
	v_mul_f32_e32 v8, v6, v8
	v_mul_f32_e32 v9, v7, v9
	v_xor_b32_e32 v9, v27, v9
	v_add_f32_e32 v22, v8, v9
	v_cndmask_b32_e32 v8, v56, v64, vcc
	v_cndmask_b32_e32 v9, v64, v56, vcc
	v_mul_f32_e32 v8, v6, v8
	v_mul_f32_e32 v9, v7, v9
	v_xor_b32_e32 v9, v27, v9
	v_add_f32_e32 v23, v8, v9
	v_cndmask_b32_e32 v8, v57, v65, vcc
	v_cndmask_b32_e32 v9, v65, v57, vcc
	v_mul_f32_e32 v8, v6, v8
	v_mul_f32_e32 v9, v7, v9
	v_xor_b32_e32 v9, v27, v9
	v_add_f32_e32 v24, v8, v9
	v_cndmask_b32_e32 v8, v58, v66, vcc
	v_cndmask_b32_e32 v9, v66, v58, vcc
	v_mul_f32_e32 v8, v6, v8
	v_mul_f32_e32 v9, v7, v9
	v_xor_b32_e32 v9, v27, v9
	v_add_f32_e32 v25, v8, v9
	v_cndmask_b32_e32 v8, v59, v67, vcc
	v_cndmask_b32_e32 v9, v67, v59, vcc
	v_mul_f32_e32 v8, v6, v8
	v_mul_f32_e32 v9, v7, v9
	v_xor_b32_e32 v9, v27, v9
	v_add_f32_e32 v26, v8, v9
	s_mov_b64 s[6:7], exec
	s_branch .LBB7_176
